# attention tile loop rewritten as two wave groups one barrier apart (MFMA segment vs softmax segment), WG-uniform nomax fast path; loads issued mid-MFMA segment, tile LDS writes after QK
# speedup vs baseline: 1.0125x; 1.0119x over previous
; __device__ __forceinline__ float bflo(unsigned u) { return __uint_as_float(u << 16); }
; __device__ __forceinline__ float bfhi(unsigned u) { return __uint_as_float(u & 0xffff0000u); }
; __device__ __forceinline__ int v_st(int k, int c) { const int kk = k; return ((kk >> 3) * 4 + (c >> 5)) * 512 + ((kk & 7) * 32 + (c & 31)) * 2; }
; __device__ __forceinline__ int v_rd_base(int lane) { return ((lane & 3) << 3) | (((lane >> 2) & 3) << 6) | (((lane >> 4) & 1) << 5) | (((lane >> 5) & 1) << 8); }
; #define A128_SLOAD(i, k0) do { sr_[i].vs0 = *reinterpret_cast<const bf16x8*>(&Vh[(long)((k0) + sr) * LDK + sc]); sr_[i].vs1 = *reinterpret_cast<const bf16x8*>(&Vh[(long)((k0) + 32 + sr) * LDK + sc]); \
;     sr_[i].ks0 = *reinterpret_cast<const bf16x8*>(&Kh[(long)((k0) + kr) * LDK + kc]); } while (0)
; __device__ __forceinline__ void unit(const bf16* __restrict__ Qb0, const bf16* __restrict__ Kh0, const bf16* __restrict__ Vh, bf16_t* Ob, int seq, char* lds, const int tid_in, const float lam, const float onem, const float* __restrict__ subw, const float* __restrict__ kmb  ) {
;     ...
;   bool nomax;
;   { float qn2 = 0.f, kb2 = 0.f;
; #pragma unroll
;     for (int d0 = 0; d0 < 4; ++d0) { const u32x4 w = __builtin_bit_cast(u32x4, qr[d0]);
; #pragma unroll
;       for (int e = 0; e < 4; ++e) { const float x0 = bflo(w[e]), x1 = bfhi(w[e]); qn2 += x0 * x0 + x1 * x1; } }
;     { auto rr = __builtin_amdgcn_permlane32_swap(__float_as_uint(qn2), __float_as_uint(qn2), false, false); qn2 = __uint_as_float(rr[0]) + __uint_as_float(rr[1]); }
; #pragma unroll
;     for (int i = 0; i < 8; ++i) kb2 += kmb[mp * 8 + i];
;     nomax = __all(qn2 * kb2 * 1.12f <= 3600.0f); }
;   const int sr = tid >> 4, sc = (tid & 15) * 8, vst0 = v_st(sr, sc), vst1 = v_st(32 + sr, sc);
;   const int kr = tid >> 3, kc = (tid & 7) * 8, kst = A128_KSWZ(kr, kc * 2);
;   const int vb0 = (int)(uintptr_t)V_lds + v_rd_base(lane);
;   struct { bf16x8 vs0, vs1, ks0; } sr_[2];
;     ...
;   f32x16 pA0, pA1, pB0, pB1; float mnA, mnB, alA, alB; bf16x8 pa0, pa1, pa2, pa3; const int NT = seq / KVBLK;
;   A128_SLOAD(0, 0); asm volatile("s_waitcnt vmcnt(0)" ::: "memory"); A128_SWRITE(0, 0); __syncthreads();
;   qkt(pA0, pA1, K_lds, qr, r32, hi); partialSM<true>(pA0, pA1, m_reg, mnA, alA, nomax);
;   A128_SLOAD(1, KVBLK); if (2 < NT) A128_SLOAD(0, 2 * KVBLK);
;   A128_SWAIT(); A128_SWRITE(1, 1); __syncthreads();
.LBB0_1109:
	v_and_b32_e32 v157, 63, v24
	v_lshlrev_b32_e32 v28, 4, v157
	v_lshlrev_b32_e32 v27, 3, v157
	v_and_b32_e32 v28, 0xc0, v28
	v_lshlrev_b32_e32 v187, 1, v157
	v_and_or_b32 v28, v27, 24, v28
	v_and_b32_e32 v29, 32, v187
	v_and_b32_e32 v27, 0x100, v27
	v_or3_b32 v44, v28, v29, v27
	v_add_u32_e32 v27, 64, v25
	v_mov_b64_e32 v[40:41], s[10:11]
	s_xor_b64 s[16:17], s[4:5], -1
	v_mad_i64_i32 v[28:29], s[4:5], v27, s33, v[40:41]
	v_add_u32_e32 v27, 0x60, v25
	v_mad_i64_i32 v[22:23], s[4:5], v26, s33, 0
	v_mad_i64_i32 v[32:33], s[4:5], v27, s33, v[40:41]
	v_add_u32_e32 v27, 64, v26
	v_mov_b64_e32 v[42:43], s[0:1]
	v_add_u32_e32 v26, 0x80, v26
	v_mad_i64_i32 v[36:37], s[0:1], v27, s33, v[42:43]
	v_mad_i64_i32 v[26:27], s[0:1], v26, s33, v[42:43]
	v_lshl_add_u64 v[36:37], v[36:37], 0, v[18:19]
	v_lshl_add_u64 v[18:19], v[26:27], 0, v[18:19]
	global_load_dwordx4 v[36:39], v[36:37], off offset:2048
	v_lshl_add_u64 v[28:29], v[28:29], 0, v[0:1]
	global_load_dwordx4 v[144:147], v[18:19], off offset:2048
	v_add_u32_e32 v18, 0xa0, v25
	v_mad_i64_i32 v[18:19], s[0:1], v18, s33, v[40:41]
	v_lshl_add_u64 v[18:19], v[18:19], 0, v[0:1]
	global_load_dwordx4 v[28:31], v[28:29], off
	v_lshl_add_u64 v[32:33], v[32:33], 0, v[0:1]
	global_load_dwordx4 v[148:151], v[18:19], off
	v_add_u32_e32 v18, 0x80, v25
	v_mad_i64_i32 v[18:19], s[0:1], v18, s33, v[40:41]
	global_load_dwordx4 v[32:35], v[32:33], off
	v_lshl_add_u64 v[18:19], v[18:19], 0, v[0:1]
	global_load_dwordx4 v[152:155], v[18:19], off
	s_lshl_b32 s3, s3, 8
	s_add_i32 s37, s3, 0
	s_lshr_b32 s100, s37, 6
	s_add_i32 s100, s100, 0x1c800
	v_mov_b32_e32 v232, s100
	v_mov_b32_e32 v233, s18
	ds_write_b32 v232, v233
	s_cmp_lg_u32 0, -1
	s_cselect_b32 s3, 0, 0
	v_add_u32_e32 v190, s3, v44
	s_addk_i32 s3, 0x4000
	v_add_u32_e32 v189, s3, v44
	s_mov_b32 s3, s93
	s_lshl_b64 s[2:3], s[2:3], 7
	v_and_b32_e32 v0, 7, v24
	v_exp_f32_e32 v178, v2
	v_exp_f32_e32 v179, v3
	v_lshl_add_u64 v[2:3], v[22:23], 0, s[2:3]
	v_lshlrev_b32_e32 v0, 4, v0
	v_lshl_add_u64 v[2:3], v[2:3], 0, v[0:1]
	v_and_b32_e32 v0, 15, v24
	v_mad_i64_i32 v[20:21], s[4:5], v25, s33, 0
	v_exp_f32_e32 v176, v4
	v_exp_f32_e32 v177, v5
	v_exp_f32_e32 v174, v6
	v_exp_f32_e32 v175, v7
	v_exp_f32_e32 v172, v8
	v_exp_f32_e32 v173, v9
	v_exp_f32_e32 v170, v10
	v_exp_f32_e32 v171, v11
	v_exp_f32_e32 v168, v12
	v_exp_f32_e32 v169, v13
	v_exp_f32_e32 v164, v14
	v_exp_f32_e32 v165, v15
	v_exp_f32_e32 v162, v16
	v_exp_f32_e32 v163, v17
	v_lshlrev_b32_e32 v0, 4, v0
	s_waitcnt vmcnt(3)
	v_lshl_add_u64 v[158:159], s[14:15], 0, v[2:3]
	v_lshl_add_u64 v[2:3], v[20:21], 0, v[0:1]
	v_mov_b32_e32 v14, v1
	v_mov_b32_e32 v15, v1
	v_lshl_add_u64 v[160:161], s[14:15], 0, v[2:3]
	v_mov_b32_e32 v0, v1
	v_mov_b32_e32 v2, v1
	v_mov_b32_e32 v3, v1
	v_mov_b32_e32 v4, v1
	s_waitcnt vmcnt(3)
	ds_write_b128 v191, v[28:31] offset:16384
	s_waitcnt vmcnt(1)
	ds_write_b128 v202, v[32:35] offset:16384
	ds_write_b128 v203, v[36:39] offset:40960
	v_mov_b32_e32 v5, v1
	v_mov_b32_e32 v6, v1
	v_mov_b32_e32 v7, v1
	v_mov_b32_e32 v8, v1
	v_mov_b32_e32 v9, v1
	v_mov_b32_e32 v10, v1
	v_mov_b32_e32 v11, v1
	v_mov_b32_e32 v12, v1
	v_mov_b32_e32 v13, v1
	v_mov_b64_e32 v[30:31], v[14:15]
	v_mov_b64_e32 v[46:47], v[14:15]
	v_mov_b64_e32 v[62:63], v[14:15]
	v_mov_b64_e32 v[78:79], v[14:15]
	s_mov_b32 s38, 4
	v_cmp_gt_u32_e64 s[0:1], 32, v157
	v_lshl_add_u32 v188, v184, 2, s37
	v_mov_b32_e32 v206, 1.0
	v_mov_b64_e32 v[28:29], v[12:13]
	v_mov_b64_e32 v[26:27], v[10:11]
	v_mov_b64_e32 v[24:25], v[8:9]
	v_mov_b64_e32 v[22:23], v[6:7]
	v_mov_b64_e32 v[20:21], v[4:5]
	v_mov_b64_e32 v[18:19], v[2:3]
	v_mov_b64_e32 v[16:17], v[0:1]
	v_mov_b64_e32 v[44:45], v[12:13]
	v_mov_b64_e32 v[42:43], v[10:11]
	v_mov_b64_e32 v[40:41], v[8:9]
	v_mov_b64_e32 v[38:39], v[6:7]
	v_mov_b64_e32 v[36:37], v[4:5]
	v_mov_b64_e32 v[34:35], v[2:3]
	v_mov_b64_e32 v[32:33], v[0:1]
	v_mov_b64_e32 v[60:61], v[12:13]
	v_mov_b64_e32 v[58:59], v[10:11]
	v_mov_b64_e32 v[56:57], v[8:9]
	v_mov_b64_e32 v[54:55], v[6:7]
	v_mov_b64_e32 v[52:53], v[4:5]
	v_mov_b64_e32 v[50:51], v[2:3]
	v_mov_b64_e32 v[48:49], v[0:1]
	v_mov_b64_e32 v[76:77], v[12:13]
	v_mov_b64_e32 v[74:75], v[10:11]
	v_mov_b64_e32 v[72:73], v[8:9]
	v_mov_b64_e32 v[70:71], v[6:7]
	v_mov_b64_e32 v[68:69], v[4:5]
	v_mov_b64_e32 v[66:67], v[2:3]
	v_mov_b64_e32 v[64:65], v[0:1]
	s_waitcnt lgkmcnt(0)
	s_barrier
	v_mov_b32_e32 v232, 0x1c800
	ds_read_b128 v[236:239], v232
	ds_read_b128 v[240:243], v232 offset:16
	s_waitcnt lgkmcnt(0)
	v_or3_b32 v236, v236, v237, v238
	v_or3_b32 v240, v240, v241, v242
	v_or3_b32 v236, v236, v239, v243
	v_or_b32_e32 v236, v236, v240
	v_cmp_eq_u32_e32 vcc, 0, v236
	s_cbranch_vccz .LBB0_1110
	s_add_u32 s100, s14, s8
	s_addc_u32 s101, s15, s9
	s_add_u32 s100, s100, 0xdfa0000
	s_addc_u32 s101, s101, 0
	v_subrev_u32_e32 v198, s14, v160
	v_subrev_u32_e32 v0, s14, v158
	v_add_u32_e32 v198, 0x1000, v198
	v_add_u32_e32 v0, 0x1a0000, v0
	v_add_u32_e32 v199, 0xd0000, v198
	s_cmp_lt_u32 s37, 0x400
	s_cbranch_scc1 .Lfa_g0
	s_barrier
; #define A128_SBAR() __builtin_amdgcn_sched_barrier(0)
; #define A128_PK4(P, BASE, OUT) do { u32x4 w = {cvt_pk_bf16(P[BASE + 0], P[BASE + 1]), cvt_pk_bf16(P[BASE + 2], P[BASE + 3]), cvt_pk_bf16(P[BASE + 4], P[BASE + 5]), cvt_pk_bf16(P[BASE + 6], P[BASE + 7])}; \
;     OUT = __builtin_bit_cast(bf16x8, w); } while (0)
; #define A128_SWAIT() asm volatile("s_waitcnt vmcnt(3)" ::: "memory")
; __device__ __forceinline__ void finishSM(f32x16& p0, f32x16& p1, float alpha, float& l_reg, bf16x8& pa0, bf16x8& pa1, bf16x8& pa2, bf16x8& pa3) {
; #pragma unroll
;   for (int r = 0; r < 16; ++r) p1[r] = __builtin_amdgcn_exp2f(p1[r]);
;   typedef float f32x8_ __attribute__((ext_vector_type(8))); typedef float f32x2_ __attribute__((ext_vector_type(2)));
;   const f32x16 s16_ = p0 + p1; const f32x8_ s8_ = s16_.lo + s16_.hi; const f32x4 s4_ = s8_.lo + s8_.hi; const f32x2_ s2_ = s4_.lo + s4_.hi;
;   float ps = s2_.x + s2_.y;
;   { auto rr = __builtin_amdgcn_permlane32_swap(__float_as_uint(ps), __float_as_uint(ps), false, false); ps = __uint_as_float(rr[0]) + __uint_as_float(rr[1]); }
;   l_reg = l_reg * alpha + ps;
;     ...
;   A128_PK4(p0, 0, pa0); A128_PK4(p0, 8, pa1); A128_PK4(p1, 0, pa2); A128_PK4(p1, 8, pa3);
;     ...
; }
; __device__ __forceinline__ void unit(const bf16* __restrict__ Qb0, const bf16* __restrict__ Kh0, const bf16* __restrict__ Vh, bf16_t* Ob, int seq, char* lds, const int tid_in, const float lam, const float onem, const float* __restrict__ subw, const float* __restrict__ kmb  ) {
;     ...
;   for (int j = 1; j + 1 < NT; j += 2) {
;     A128_SBAR(); qkt(pB0, pB1, K_lds + SHM_K, qr, r32, hi);
;     finishSM(pA0, pA1, alA, l_reg, pa0, pa1, pa2, pa3); A128_SBAR();
;     A128_SLOAD(1, (j + 2) * KVBLK); A128_SBAR();
;     pv_d0(o, vb0, pa0, pa1, pa2, pa3); partialSM(pB0, pB1, m_reg, mnB, alB, nomax);
;     __syncthreads(); A128_SWAIT(); A128_SWRITE(0, 0);
;     if (!nomax) A128_RESC(alB); __syncthreads();
;     A128_SBAR(); qkt(pA0, pA1, K_lds, qr, r32, hi);
;     finishSM(pB0, pB1, alB, l_reg, pa0, pa1, pa2, pa3); A128_SBAR();
;     if (j + 3 < NT) A128_SLOAD(0, (j + 3) * KVBLK); A128_SBAR();
;     pv_d0(o, vb0 + (int)SHM_V, pa0, pa1, pa2, pa3); partialSM(pA0, pA1, m_reg, mnA, alA, nomax);
;     __syncthreads(); A128_SWAIT(); A128_SWRITE(1, 1);
;     if (!nomax) A128_RESC(alA); __syncthreads();
;   }
.Lfa_g0:
	global_load_dwordx4 v[152:155], v198, s[100:101]
	global_load_dwordx4 v[148:151], v199, s[100:101]
	s_add_u32 s100, s100, 0x1a0000
	s_addc_u32 s101, s101, 0
	global_load_dwordx4 v[232:235], v198, s[100:101]
	global_load_dwordx4 v[236:239], v199, s[100:101]
	global_load_dwordx4 v[240:243], v0, s[100:101] offset:2048
	s_add_u32 s100, s100, 0x1a0000
	s_addc_u32 s101, s101, 0
	v_exp_f32_e32 v80, v80
	v_exp_f32_e32 v81, v81
	v_exp_f32_e32 v82, v82
	v_exp_f32_e32 v83, v83
	v_exp_f32_e32 v84, v84
	v_exp_f32_e32 v85, v85
	v_exp_f32_e32 v86, v86
	v_exp_f32_e32 v87, v87
	v_exp_f32_e32 v88, v88
	v_exp_f32_e32 v89, v89
	v_exp_f32_e32 v90, v90
	v_exp_f32_e32 v91, v91
	v_exp_f32_e32 v92, v92
	v_exp_f32_e32 v93, v93
	v_exp_f32_e32 v94, v94
	v_exp_f32_e32 v95, v95
	v_pk_add_f32 v[2:3], v[178:179], v[80:81]
	v_pk_add_f32 v[4:5], v[176:177], v[82:83]
	v_pk_add_f32 v[6:7], v[174:175], v[84:85]
	v_pk_add_f32 v[8:9], v[172:173], v[86:87]
	v_pk_add_f32 v[10:11], v[170:171], v[88:89]
	v_pk_add_f32 v[12:13], v[168:169], v[90:91]
	v_pk_add_f32 v[14:15], v[164:165], v[92:93]
	v_pk_add_f32 v[194:195], v[162:163], v[94:95]
	v_pk_add_f32 v[2:3], v[2:3], v[10:11]
	v_pk_add_f32 v[4:5], v[4:5], v[12:13]
	v_pk_add_f32 v[6:7], v[6:7], v[14:15]
	v_pk_add_f32 v[8:9], v[8:9], v[194:195]
	v_pk_add_f32 v[2:3], v[2:3], v[6:7]
	v_pk_add_f32 v[4:5], v[4:5], v[8:9]
	s_nop 0
	v_pk_add_f32 v[2:3], v[2:3], v[4:5]
	s_nop 0
	v_add_f32_e32 v2, v2, v3
	s_nop 0
	v_mov_b32_e32 v3, v2
	s_nop 1
	v_permlane32_swap_b32_e32 v2, v3
	s_nop 1
	v_add_f32_e32 v2, v2, v3
	s_nop 0
	v_add_f32_e32 v186, v186, v2
	v_cvt_pk_bf16_f32 v2, v80, v81
	v_cvt_pk_bf16_f32 v3, v82, v83
	v_cvt_pk_bf16_f32 v4, v84, v85
	v_cvt_pk_bf16_f32 v5, v86, v87
	v_cvt_pk_bf16_f32 v6, v88, v89
	v_cvt_pk_bf16_f32 v7, v90, v91
	v_cvt_pk_bf16_f32 v8, v92, v93
	v_cvt_pk_bf16_f32 v9, v94, v95
	s_nop 0
	v_cvt_pk_bf16_f32 v80, v178, v179
	v_cvt_pk_bf16_f32 v81, v176, v177
	v_cvt_pk_bf16_f32 v82, v174, v175
	v_cvt_pk_bf16_f32 v83, v172, v173
	v_cvt_pk_bf16_f32 v84, v170, v171
	v_cvt_pk_bf16_f32 v85, v168, v169
	v_cvt_pk_bf16_f32 v86, v164, v165
	v_cvt_pk_bf16_f32 v87, v162, v163
	v_mov_b32_e32 v88, v2
	v_mov_b32_e32 v89, v3
	v_mov_b32_e32 v90, v4
	v_mov_b32_e32 v91, v5
	v_mov_b32_e32 v92, v6
	v_mov_b32_e32 v93, v7
	v_mov_b32_e32 v94, v8
	v_mov_b32_e32 v95, v9
.Lfa_loop:
	s_barrier
	s_setprio 1
	ds_read_b128 v[2:5], v204 offset:40960
	ds_read_b128 v[6:9], v204 offset:45056
	ds_read_b128 v[10:13], v205 offset:40960
	ds_read_b128 v[162:165], v205 offset:45056
	s_waitcnt lgkmcnt(2)
	v_mfma_f32_32x32x16_bf16 v[112:127], v[2:5], v[140:143], 0
	ds_read_b128 v[168:171], v192 offset:40960
	ds_read_b128 v[172:175], v192 offset:45056
	v_mfma_f32_32x32x16_bf16 v[96:111], v[6:9], v[140:143], 0
	ds_read_b128 v[176:179], v193 offset:40960
	ds_read_b128 v[194:197], v193 offset:45056
	s_waitcnt lgkmcnt(4)
	v_mfma_f32_32x32x16_bf16 v[112:127], v[10:13], v[136:139], v[112:127]
	ds_read_b64_tr_b16 v[210:211], v190 offset:0x0
	ds_read_b64_tr_b16 v[212:213], v190 offset:0x800
	ds_read_b64_tr_b16 v[214:215], v190 offset:0x1000
	v_mfma_f32_32x32x16_bf16 v[96:111], v[162:165], v[136:139], v[96:111]
	ds_read_b64_tr_b16 v[216:217], v190 offset:0x1800
	ds_read_b64_tr_b16 v[244:245], v190 offset:0x2000
	ds_read_b64_tr_b16 v[246:247], v190 offset:0x2800
	s_waitcnt lgkmcnt(8)
	v_mfma_f32_32x32x16_bf16 v[112:127], v[168:171], v[132:135], v[112:127]
	ds_read_b64_tr_b16 v[248:249], v190 offset:0x3000
	ds_read_b64_tr_b16 v[250:251], v190 offset:0x3800
	v_mfma_f32_32x32x16_bf16 v[96:111], v[172:175], v[132:135], v[96:111]
	ds_read_b64_tr_b16 v[2:3], v190 offset:0x200
	ds_read_b64_tr_b16 v[4:5], v190 offset:0xa00
	ds_read_b64_tr_b16 v[6:7], v190 offset:0x1200
	s_waitcnt lgkmcnt(11)
	v_mfma_f32_32x32x16_bf16 v[112:127], v[176:179], v[128:131], v[112:127]
	ds_read_b64_tr_b16 v[8:9], v190 offset:0x1a00
	ds_read_b64_tr_b16 v[10:11], v190 offset:0x2200
	ds_read_b64_tr_b16 v[12:13], v190 offset:0x2a00
	v_mfma_f32_32x32x16_bf16 v[96:111], v[194:197], v[128:131], v[96:111]
	ds_read_b64_tr_b16 v[162:163], v190 offset:0x3200
	ds_read_b64_tr_b16 v[164:165], v190 offset:0x3a00
	s_waitcnt vmcnt(3)
	ds_write_b128 v203, v[144:147] offset:32768
	ds_write_b128 v191, v[152:155] offset:16384
	ds_write_b128 v202, v[148:151] offset:16384
	s_waitcnt lgkmcnt(11)
	v_mfma_f32_32x32x16_bf16 v[16:31], v[80:83], v[210:213], v[16:31]
	ds_read_b64_tr_b16 v[210:211], v190 offset:0x400
	ds_read_b64_tr_b16 v[212:213], v190 offset:0xc00
	v_mfma_f32_32x32x16_bf16 v[16:31], v[84:87], v[214:217], v[16:31]
	ds_read_b64_tr_b16 v[214:215], v190 offset:0x1400
	ds_read_b64_tr_b16 v[216:217], v190 offset:0x1c00
	v_mfma_f32_32x32x16_bf16 v[16:31], v[88:91], v[244:247], v[16:31]
	ds_read_b64_tr_b16 v[244:245], v190 offset:0x2400
	ds_read_b64_tr_b16 v[246:247], v190 offset:0x2c00
	v_mfma_f32_32x32x16_bf16 v[16:31], v[92:95], v[248:251], v[16:31]
	ds_read_b64_tr_b16 v[248:249], v190 offset:0x3400
	ds_read_b64_tr_b16 v[250:251], v190 offset:0x3c00
	s_waitcnt lgkmcnt(11)
	v_mfma_f32_32x32x16_bf16 v[32:47], v[80:83], v[2:5], v[32:47]
	ds_read_b64_tr_b16 v[2:3], v190 offset:0x600
	ds_read_b64_tr_b16 v[4:5], v190 offset:0xe00
	v_mfma_f32_32x32x16_bf16 v[32:47], v[84:87], v[6:9], v[32:47]
	ds_read_b64_tr_b16 v[6:7], v190 offset:0x1600
	ds_read_b64_tr_b16 v[8:9], v190 offset:0x1e00
	v_mfma_f32_32x32x16_bf16 v[32:47], v[88:91], v[10:13], v[32:47]
	ds_read_b64_tr_b16 v[10:11], v190 offset:0x2600
	ds_read_b64_tr_b16 v[12:13], v190 offset:0x2e00
	v_mfma_f32_32x32x16_bf16 v[32:47], v[92:95], v[162:165], v[32:47]
	ds_read_b64_tr_b16 v[162:163], v190 offset:0x3600
	ds_read_b64_tr_b16 v[164:165], v190 offset:0x3e00
	global_load_dwordx4 v[152:155], v198, s[100:101]
	global_load_dwordx4 v[148:151], v199, s[100:101]
	global_load_dwordx4 v[144:147], v0, s[100:101] offset:2048
	s_add_u32 s100, s100, 0x1a0000
	s_addc_u32 s101, s101, 0
	s_waitcnt lgkmcnt(8)
	v_mfma_f32_32x32x16_bf16 v[48:63], v[80:83], v[210:213], v[48:63]
	v_mfma_f32_32x32x16_bf16 v[48:63], v[84:87], v[214:217], v[48:63]
	v_mfma_f32_32x32x16_bf16 v[48:63], v[88:91], v[244:247], v[48:63]
	v_mfma_f32_32x32x16_bf16 v[48:63], v[92:95], v[248:251], v[48:63]
	s_waitcnt lgkmcnt(0)
	v_mfma_f32_32x32x16_bf16 v[64:79], v[80:83], v[2:5], v[64:79]
	v_mfma_f32_32x32x16_bf16 v[64:79], v[84:87], v[6:9], v[64:79]
	v_mfma_f32_32x32x16_bf16 v[64:79], v[88:91], v[10:13], v[64:79]
	v_mfma_f32_32x32x16_bf16 v[64:79], v[92:95], v[162:165], v[64:79]
	s_setprio 0
	s_barrier
; #define A128_SBAR() __builtin_amdgcn_sched_barrier(0)
; #define A128_PK4(P, BASE, OUT) do { u32x4 w = {cvt_pk_bf16(P[BASE + 0], P[BASE + 1]), cvt_pk_bf16(P[BASE + 2], P[BASE + 3]), cvt_pk_bf16(P[BASE + 4], P[BASE + 5]), cvt_pk_bf16(P[BASE + 6], P[BASE + 7])}; \
;     OUT = __builtin_bit_cast(bf16x8, w); } while (0)
; #define A128_SWAIT() asm volatile("s_waitcnt vmcnt(3)" ::: "memory")
; __device__ __forceinline__ void finishSM(f32x16& p0, f32x16& p1, float alpha, float& l_reg, bf16x8& pa0, bf16x8& pa1, bf16x8& pa2, bf16x8& pa3) {
; #pragma unroll
;   for (int r = 0; r < 16; ++r) p1[r] = __builtin_amdgcn_exp2f(p1[r]);
;   typedef float f32x8_ __attribute__((ext_vector_type(8))); typedef float f32x2_ __attribute__((ext_vector_type(2)));
;   const f32x16 s16_ = p0 + p1; const f32x8_ s8_ = s16_.lo + s16_.hi; const f32x4 s4_ = s8_.lo + s8_.hi; const f32x2_ s2_ = s4_.lo + s4_.hi;
;   float ps = s2_.x + s2_.y;
;   { auto rr = __builtin_amdgcn_permlane32_swap(__float_as_uint(ps), __float_as_uint(ps), false, false); ps = __uint_as_float(rr[0]) + __uint_as_float(rr[1]); }
;   l_reg = l_reg * alpha + ps;
;     ...
;   A128_PK4(p0, 0, pa0); A128_PK4(p0, 8, pa1); A128_PK4(p1, 0, pa2); A128_PK4(p1, 8, pa3);
;     ...
; }
; __device__ __forceinline__ void unit(const bf16* __restrict__ Qb0, const bf16* __restrict__ Kh0, const bf16* __restrict__ Vh, bf16_t* Ob, int seq, char* lds, const int tid_in, const float lam, const float onem, const float* __restrict__ subw, const float* __restrict__ kmb  ) {
;     ...
;   for (int j = 1; j + 1 < NT; j += 2) {
;     A128_SBAR(); qkt(pB0, pB1, K_lds + SHM_K, qr, r32, hi);
;     finishSM(pA0, pA1, alA, l_reg, pa0, pa1, pa2, pa3); A128_SBAR();
;     A128_SLOAD(1, (j + 2) * KVBLK); A128_SBAR();
;     pv_d0(o, vb0, pa0, pa1, pa2, pa3); partialSM(pB0, pB1, m_reg, mnB, alB, nomax);
;     __syncthreads(); A128_SWAIT(); A128_SWRITE(0, 0);
;     if (!nomax) A128_RESC(alB); __syncthreads();
;     A128_SBAR(); qkt(pA0, pA1, K_lds, qr, r32, hi);
;     finishSM(pB0, pB1, alB, l_reg, pa0, pa1, pa2, pa3); A128_SBAR();
;     if (j + 3 < NT) A128_SLOAD(0, (j + 3) * KVBLK); A128_SBAR();
;     pv_d0(o, vb0 + (int)SHM_V, pa0, pa1, pa2, pa3); partialSM(pA0, pA1, m_reg, mnA, alA, nomax);
;     __syncthreads(); A128_SWAIT(); A128_SWRITE(1, 1);
;     if (!nomax) A128_RESC(alA); __syncthreads();
;   }
	v_exp_f32_e32 v96, v96
	v_exp_f32_e32 v97, v97
	v_exp_f32_e32 v98, v98
	v_exp_f32_e32 v99, v99
	v_exp_f32_e32 v100, v100
	v_exp_f32_e32 v101, v101
	v_exp_f32_e32 v102, v102
	v_exp_f32_e32 v103, v103
	v_exp_f32_e32 v104, v104
	v_exp_f32_e32 v105, v105
	v_exp_f32_e32 v106, v106
	v_exp_f32_e32 v107, v107
	v_exp_f32_e32 v108, v108
	v_exp_f32_e32 v109, v109
	v_exp_f32_e32 v110, v110
	v_exp_f32_e32 v111, v111
	v_exp_f32_e32 v112, v112
	v_exp_f32_e32 v113, v113
	v_exp_f32_e32 v114, v114
	v_exp_f32_e32 v115, v115
	v_exp_f32_e32 v116, v116
	v_exp_f32_e32 v117, v117
	v_exp_f32_e32 v118, v118
	v_exp_f32_e32 v119, v119
	v_exp_f32_e32 v120, v120
	v_exp_f32_e32 v121, v121
	v_exp_f32_e32 v122, v122
	v_exp_f32_e32 v123, v123
	v_exp_f32_e32 v124, v124
	v_exp_f32_e32 v125, v125
	v_exp_f32_e32 v126, v126
	v_exp_f32_e32 v127, v127
	v_pk_add_f32 v[2:3], v[112:113], v[96:97]
	v_pk_add_f32 v[4:5], v[114:115], v[98:99]
	v_pk_add_f32 v[6:7], v[116:117], v[100:101]
	v_pk_add_f32 v[8:9], v[118:119], v[102:103]
	v_pk_add_f32 v[10:11], v[120:121], v[104:105]
	v_pk_add_f32 v[12:13], v[122:123], v[106:107]
	v_pk_add_f32 v[14:15], v[124:125], v[108:109]
	v_pk_add_f32 v[194:195], v[126:127], v[110:111]
	v_pk_add_f32 v[2:3], v[2:3], v[10:11]
	v_pk_add_f32 v[4:5], v[4:5], v[12:13]
	v_pk_add_f32 v[6:7], v[6:7], v[14:15]
	v_pk_add_f32 v[8:9], v[8:9], v[194:195]
	v_pk_add_f32 v[2:3], v[2:3], v[6:7]
	v_pk_add_f32 v[4:5], v[4:5], v[8:9]
	s_nop 0
	v_pk_add_f32 v[2:3], v[2:3], v[4:5]
	s_nop 0
	v_add_f32_e32 v2, v2, v3
	s_nop 0
	v_mov_b32_e32 v3, v2
	s_nop 1
	v_permlane32_swap_b32_e32 v2, v3
	s_nop 1
	v_add_f32_e32 v2, v2, v3
	s_nop 0
	v_add_f32_e32 v186, v186, v2
	v_cvt_pk_bf16_f32 v80, v112, v113
	v_cvt_pk_bf16_f32 v81, v114, v115
	v_cvt_pk_bf16_f32 v82, v116, v117
	v_cvt_pk_bf16_f32 v83, v118, v119
	v_cvt_pk_bf16_f32 v84, v120, v121
	v_cvt_pk_bf16_f32 v85, v122, v123
	v_cvt_pk_bf16_f32 v86, v124, v125
	v_cvt_pk_bf16_f32 v87, v126, v127
	v_cvt_pk_bf16_f32 v88, v96, v97
	v_cvt_pk_bf16_f32 v89, v98, v99
	v_cvt_pk_bf16_f32 v90, v100, v101
	v_cvt_pk_bf16_f32 v91, v102, v103
	v_cvt_pk_bf16_f32 v92, v104, v105
	v_cvt_pk_bf16_f32 v93, v106, v107
	v_cvt_pk_bf16_f32 v94, v108, v109
	v_cvt_pk_bf16_f32 v95, v110, v111
	s_barrier
	s_setprio 1
	ds_read_b128 v[2:5], v204 offset:32768
	ds_read_b128 v[6:9], v204 offset:36864
	ds_read_b128 v[10:13], v205 offset:32768
	ds_read_b128 v[162:165], v205 offset:36864
	s_waitcnt lgkmcnt(2)
	v_mfma_f32_32x32x16_bf16 v[112:127], v[2:5], v[140:143], 0
	ds_read_b128 v[168:171], v192 offset:32768
	ds_read_b128 v[172:175], v192 offset:36864
	v_mfma_f32_32x32x16_bf16 v[96:111], v[6:9], v[140:143], 0
	ds_read_b128 v[176:179], v193 offset:32768
	ds_read_b128 v[194:197], v193 offset:36864
	s_waitcnt lgkmcnt(4)
	v_mfma_f32_32x32x16_bf16 v[112:127], v[10:13], v[136:139], v[112:127]
	ds_read_b64_tr_b16 v[210:211], v189 offset:0x0
	ds_read_b64_tr_b16 v[212:213], v189 offset:0x800
	ds_read_b64_tr_b16 v[214:215], v189 offset:0x1000
	v_mfma_f32_32x32x16_bf16 v[96:111], v[162:165], v[136:139], v[96:111]
	ds_read_b64_tr_b16 v[216:217], v189 offset:0x1800
	ds_read_b64_tr_b16 v[244:245], v189 offset:0x2000
	ds_read_b64_tr_b16 v[246:247], v189 offset:0x2800
	s_waitcnt lgkmcnt(8)
	v_mfma_f32_32x32x16_bf16 v[112:127], v[168:171], v[132:135], v[112:127]
	ds_read_b64_tr_b16 v[248:249], v189 offset:0x3000
	ds_read_b64_tr_b16 v[250:251], v189 offset:0x3800
	v_mfma_f32_32x32x16_bf16 v[96:111], v[172:175], v[132:135], v[96:111]
	ds_read_b64_tr_b16 v[2:3], v189 offset:0x200
	ds_read_b64_tr_b16 v[4:5], v189 offset:0xa00
	ds_read_b64_tr_b16 v[6:7], v189 offset:0x1200
	s_waitcnt lgkmcnt(11)
	v_mfma_f32_32x32x16_bf16 v[112:127], v[176:179], v[128:131], v[112:127]
	ds_read_b64_tr_b16 v[8:9], v189 offset:0x1a00
	ds_read_b64_tr_b16 v[10:11], v189 offset:0x2200
	ds_read_b64_tr_b16 v[12:13], v189 offset:0x2a00
	v_mfma_f32_32x32x16_bf16 v[96:111], v[194:197], v[128:131], v[96:111]
	ds_read_b64_tr_b16 v[162:163], v189 offset:0x3200
	ds_read_b64_tr_b16 v[164:165], v189 offset:0x3a00
	s_waitcnt vmcnt(3)
	ds_write_b128 v203, v[240:243] offset:40960
	ds_write_b128 v191, v[232:235]
	ds_write_b128 v202, v[236:239]
	s_waitcnt lgkmcnt(11)
	v_mfma_f32_32x32x16_bf16 v[16:31], v[80:83], v[210:213], v[16:31]
	ds_read_b64_tr_b16 v[210:211], v189 offset:0x400
	ds_read_b64_tr_b16 v[212:213], v189 offset:0xc00
	v_mfma_f32_32x32x16_bf16 v[16:31], v[84:87], v[214:217], v[16:31]
	ds_read_b64_tr_b16 v[214:215], v189 offset:0x1400
	ds_read_b64_tr_b16 v[216:217], v189 offset:0x1c00
	v_mfma_f32_32x32x16_bf16 v[16:31], v[88:91], v[244:247], v[16:31]
	ds_read_b64_tr_b16 v[244:245], v189 offset:0x2400
	ds_read_b64_tr_b16 v[246:247], v189 offset:0x2c00
	v_mfma_f32_32x32x16_bf16 v[16:31], v[92:95], v[248:251], v[16:31]
	ds_read_b64_tr_b16 v[248:249], v189 offset:0x3400
	ds_read_b64_tr_b16 v[250:251], v189 offset:0x3c00
	s_waitcnt lgkmcnt(11)
	v_mfma_f32_32x32x16_bf16 v[32:47], v[80:83], v[2:5], v[32:47]
	ds_read_b64_tr_b16 v[2:3], v189 offset:0x600
	ds_read_b64_tr_b16 v[4:5], v189 offset:0xe00
	v_mfma_f32_32x32x16_bf16 v[32:47], v[84:87], v[6:9], v[32:47]
	ds_read_b64_tr_b16 v[6:7], v189 offset:0x1600
	ds_read_b64_tr_b16 v[8:9], v189 offset:0x1e00
	v_mfma_f32_32x32x16_bf16 v[32:47], v[88:91], v[10:13], v[32:47]
	ds_read_b64_tr_b16 v[10:11], v189 offset:0x2600
	ds_read_b64_tr_b16 v[12:13], v189 offset:0x2e00
	v_mfma_f32_32x32x16_bf16 v[32:47], v[92:95], v[162:165], v[32:47]
	ds_read_b64_tr_b16 v[162:163], v189 offset:0x3600
	ds_read_b64_tr_b16 v[164:165], v189 offset:0x3e00
	global_load_dwordx4 v[232:235], v198, s[100:101]
	global_load_dwordx4 v[236:239], v199, s[100:101]
	global_load_dwordx4 v[240:243], v0, s[100:101] offset:2048
	s_add_u32 s100, s100, 0x1a0000
	s_addc_u32 s101, s101, 0
	s_waitcnt lgkmcnt(8)
	v_mfma_f32_32x32x16_bf16 v[48:63], v[80:83], v[210:213], v[48:63]
	v_mfma_f32_32x32x16_bf16 v[48:63], v[84:87], v[214:217], v[48:63]
	v_mfma_f32_32x32x16_bf16 v[48:63], v[88:91], v[244:247], v[48:63]
	v_mfma_f32_32x32x16_bf16 v[48:63], v[92:95], v[248:251], v[48:63]
	s_waitcnt lgkmcnt(0)
	v_mfma_f32_32x32x16_bf16 v[64:79], v[80:83], v[2:5], v[64:79]
	v_mfma_f32_32x32x16_bf16 v[64:79], v[84:87], v[6:9], v[64:79]
	v_mfma_f32_32x32x16_bf16 v[64:79], v[88:91], v[10:13], v[64:79]
	v_mfma_f32_32x32x16_bf16 v[64:79], v[92:95], v[162:165], v[64:79]
	s_setprio 0
	s_barrier
; #define A128_SBAR() __builtin_amdgcn_sched_barrier(0)
; #define A128_SLOAD(i, k0) do { sr_[i].vs0 = *reinterpret_cast<const bf16x8*>(&Vh[(long)((k0) + sr) * LDK + sc]); sr_[i].vs1 = *reinterpret_cast<const bf16x8*>(&Vh[(long)((k0) + 32 + sr) * LDK + sc]); \
;     sr_[i].ks0 = *reinterpret_cast<const bf16x8*>(&Kh[(long)((k0) + kr) * LDK + kc]); } while (0)
; #define A128_SWRITE(b, i) do { *(bf16x8*)(V_lds + (b) * SHM_V + vst0) = sr_[i].vs0; *(bf16x8*)(V_lds + (b) * SHM_V + vst1) = sr_[i].vs1; *(bf16x8*)(K_lds + (b) * SHM_K + kst) = sr_[i].ks0; } while (0)
; #define A128_SWAIT() asm volatile("s_waitcnt vmcnt(3)" ::: "memory")
; #define A128_RESC(a) do { if (__any((a) < 1.f)) { if (hi == 0) al_l[r32] = (a); asm volatile("s_waitcnt lgkmcnt(0)" ::: "memory"); \
;     _Pragma("unroll") for (int d = 0; d < 4; ++d) _Pragma("unroll") for (int r = 0; r < 16; ++r) o[d][r] *= al_l[crow(r, hi)]; } } while (0)
; __device__ __forceinline__ void unit(const bf16* __restrict__ Qb0, const bf16* __restrict__ Kh0, const bf16* __restrict__ Vh, bf16_t* Ob, int seq, char* lds, const int tid_in, const float lam, const float onem, const float* __restrict__ subw, const float* __restrict__ kmb  ) {
;     ...
;   for (int j = 1; j + 1 < NT; j += 2) {
;     A128_SBAR(); qkt(pB0, pB1, K_lds + SHM_K, qr, r32, hi);
;     finishSM(pA0, pA1, alA, l_reg, pa0, pa1, pa2, pa3); A128_SBAR();
;     A128_SLOAD(1, (j + 2) * KVBLK); A128_SBAR();
;     pv_d0(o, vb0, pa0, pa1, pa2, pa3); partialSM(pB0, pB1, m_reg, mnB, alB, nomax);
;     __syncthreads(); A128_SWAIT(); A128_SWRITE(0, 0);
;     if (!nomax) A128_RESC(alB); __syncthreads();
;     A128_SBAR(); qkt(pA0, pA1, K_lds, qr, r32, hi);
;     finishSM(pB0, pB1, alB, l_reg, pa0, pa1, pa2, pa3); A128_SBAR();
;     if (j + 3 < NT) A128_SLOAD(0, (j + 3) * KVBLK); A128_SBAR();
;     pv_d0(o, vb0 + (int)SHM_V, pa0, pa1, pa2, pa3); partialSM(pA0, pA1, m_reg, mnA, alA, nomax);
;     __syncthreads(); A128_SWAIT(); A128_SWRITE(1, 1);
;     if (!nomax) A128_RESC(alA); __syncthreads();
;   }
;   A128_SBAR(); qkt(pB0, pB1, K_lds + SHM_K, qr, r32, hi);
;   finishSM(pA0, pA1, alA, l_reg, pa0, pa1, pa2, pa3); A128_SBAR();
;   pv_d0(o, vb0, pa0, pa1, pa2, pa3); partialSM(pB0, pB1, m_reg, mnB, alB, nomax);
;   __syncthreads(); if (!nomax) A128_RESC(alB);
;   finishSM(pB0, pB1, alB, l_reg, pa0, pa1, pa2, pa3); A128_SBAR();
;   pv_d0(o, vb0 + (int)SHM_V, pa0, pa1, pa2, pa3);
	s_cmp_ge_u32 s38, s27
	s_cbranch_scc1 .Lfa_exit
	s_add_i32 s38, s38, 2
	v_exp_f32_e32 v96, v96
	v_exp_f32_e32 v97, v97
	v_exp_f32_e32 v98, v98
	v_exp_f32_e32 v99, v99
	v_exp_f32_e32 v100, v100
	v_exp_f32_e32 v101, v101
	v_exp_f32_e32 v102, v102
	v_exp_f32_e32 v103, v103
	v_exp_f32_e32 v104, v104
	v_exp_f32_e32 v105, v105
	v_exp_f32_e32 v106, v106
	v_exp_f32_e32 v107, v107
	v_exp_f32_e32 v108, v108
	v_exp_f32_e32 v109, v109
	v_exp_f32_e32 v110, v110
	v_exp_f32_e32 v111, v111
	v_exp_f32_e32 v112, v112
	v_exp_f32_e32 v113, v113
	v_exp_f32_e32 v114, v114
	v_exp_f32_e32 v115, v115
	v_exp_f32_e32 v116, v116
	v_exp_f32_e32 v117, v117
	v_exp_f32_e32 v118, v118
	v_exp_f32_e32 v119, v119
	v_exp_f32_e32 v120, v120
	v_exp_f32_e32 v121, v121
	v_exp_f32_e32 v122, v122
	v_exp_f32_e32 v123, v123
	v_exp_f32_e32 v124, v124
	v_exp_f32_e32 v125, v125
	v_exp_f32_e32 v126, v126
	v_exp_f32_e32 v127, v127
	v_pk_add_f32 v[2:3], v[112:113], v[96:97]
	v_pk_add_f32 v[4:5], v[114:115], v[98:99]
	v_pk_add_f32 v[6:7], v[116:117], v[100:101]
	v_pk_add_f32 v[8:9], v[118:119], v[102:103]
	v_pk_add_f32 v[10:11], v[120:121], v[104:105]
	v_pk_add_f32 v[12:13], v[122:123], v[106:107]
	v_pk_add_f32 v[14:15], v[124:125], v[108:109]
	v_pk_add_f32 v[194:195], v[126:127], v[110:111]
	v_pk_add_f32 v[2:3], v[2:3], v[10:11]
	v_pk_add_f32 v[4:5], v[4:5], v[12:13]
	v_pk_add_f32 v[6:7], v[6:7], v[14:15]
	v_pk_add_f32 v[8:9], v[8:9], v[194:195]
	v_pk_add_f32 v[2:3], v[2:3], v[6:7]
	v_pk_add_f32 v[4:5], v[4:5], v[8:9]
	s_nop 0
	v_pk_add_f32 v[2:3], v[2:3], v[4:5]
	s_nop 0
	v_add_f32_e32 v2, v2, v3
	s_nop 0
	v_mov_b32_e32 v3, v2
	s_nop 1
	v_permlane32_swap_b32_e32 v2, v3
	s_nop 1
	v_add_f32_e32 v2, v2, v3
	s_nop 0
	v_add_f32_e32 v186, v186, v2
	v_cvt_pk_bf16_f32 v80, v112, v113
	v_cvt_pk_bf16_f32 v81, v114, v115
	v_cvt_pk_bf16_f32 v82, v116, v117
	v_cvt_pk_bf16_f32 v83, v118, v119
	v_cvt_pk_bf16_f32 v84, v120, v121
	v_cvt_pk_bf16_f32 v85, v122, v123
	v_cvt_pk_bf16_f32 v86, v124, v125
	v_cvt_pk_bf16_f32 v87, v126, v127
	v_cvt_pk_bf16_f32 v88, v96, v97
	v_cvt_pk_bf16_f32 v89, v98, v99
	v_cvt_pk_bf16_f32 v90, v100, v101
	v_cvt_pk_bf16_f32 v91, v102, v103
	v_cvt_pk_bf16_f32 v92, v104, v105
	v_cvt_pk_bf16_f32 v93, v106, v107
	v_cvt_pk_bf16_f32 v94, v108, v109
	v_cvt_pk_bf16_f32 v95, v110, v111
	s_branch .Lfa_loop
.Lfa_exit:
	v_exp_f32_e32 v178, v112
	v_exp_f32_e32 v179, v113
	v_exp_f32_e32 v176, v114
	v_exp_f32_e32 v177, v115
	v_exp_f32_e32 v174, v116
	v_exp_f32_e32 v175, v117
	v_exp_f32_e32 v172, v118
	v_exp_f32_e32 v173, v119
	v_exp_f32_e32 v170, v120
	v_exp_f32_e32 v171, v121
	v_exp_f32_e32 v168, v122
	v_exp_f32_e32 v169, v123
	v_exp_f32_e32 v164, v124
	v_exp_f32_e32 v165, v125
	v_exp_f32_e32 v162, v126
	v_exp_f32_e32 v163, v127
	v_mov_b32_e32 v80, v96
	v_mov_b32_e32 v81, v97
	v_mov_b32_e32 v82, v98
	v_mov_b32_e32 v83, v99
	v_mov_b32_e32 v84, v100
	v_mov_b32_e32 v85, v101
	v_mov_b32_e32 v86, v102
	v_mov_b32_e32 v87, v103
	v_mov_b32_e32 v88, v104
	v_mov_b32_e32 v89, v105
	v_mov_b32_e32 v90, v106
	v_mov_b32_e32 v91, v107
	v_mov_b32_e32 v92, v108
	v_mov_b32_e32 v93, v109
	v_mov_b32_e32 v94, v110
	v_mov_b32_e32 v95, v111
	v_mov_b32_e32 v15, 1.0
	s_mov_b64 s[4:5], -1
	s_mov_b64 s[2:3], -1
	s_cmp_ge_u32 s37, 0x400
	s_cbranch_scc1 .Lfa_x1
	s_barrier
.Lfa_x1:
	s_waitcnt vmcnt(0)
	ds_write_b128 v191, v[152:155] offset:16384
	ds_write_b128 v202, v[148:151] offset:16384
	s_waitcnt lgkmcnt(0)
	s_branch .LBB0_1134
